# norm1 pass context-row path: same hoist of the gvec/scale/shift loads of column groups 1-3 as in the norm2 pass
# baseline (speedup 1.0000x reference)
; __device__ __forceinline__ void norm_mod_pass(const float* xlat, float* xctx, const float* gvec, const float* modL, int ch_sh, int ch_sc, bf16* H, int nrows, int gw, int NGW, int lane, const bf16* x1a, const bf16* x1b, const float* P, int nsplit, const float* pgate) {
;     ...
;         for (int r = TLAT + gw; r < nrows; r += NGW) {
;             f32x4 v[4], pp_[4][11];
; #pragma unroll
;             for (int jj = 0; jj < 4; ++jj) { const int cidx = 4 * lane + 256 * jj; v[jj] = *(const f32x4*)(xctx + (size_t)(r - TLAT) * DM + cidx);
; #pragma unroll
;                 for (int s = 0; s < 11; ++s) { const int se = s < nsplit ? s : nsplit - 1; pp_[jj][s] = *(const f32x4*)(P + ((size_t)se * TCTX + (r - TLAT)) * DM + cidx); } }
;             float ss = 0.f;
; #pragma unroll
;             for (int jj = 0; jj < 4; ++jj) { const int cidx = 4 * lane + 256 * jj; f32x4 a = (f32x4){0.f, 0.f, 0.f, 0.f};
; #pragma unroll
;                 for (int s = 0; s < 11; ++s) a += pp_[jj][s] * (s < nsplit ? 1.f : 0.f);
;                 v[jj] += *(const f32x4*)(pgate + cidx) * a; *(f32x4*)(xctx + (size_t)(r - TLAT) * DM + cidx) = v[jj];
.LBB0_617:
	v_lshl_add_u64 v[12:13], s[30:31], 0, v[74:75]
	v_add_co_u32_e32 v76, vcc, 0x200000, v12
	s_add_i32 s6, s6, s60
	s_nop 0
	v_addc_co_u32_e32 v77, vcc, 0, v13, vcc
	v_add_co_u32_e32 v78, vcc, 0x19800000, v12
	global_load_dwordx4 v[0:3], v[76:77], off
	s_nop 0
	v_addc_co_u32_e32 v79, vcc, 0, v13, vcc
	v_add_co_u32_e32 v80, vcc, 0x19c00000, v12
	global_load_dwordx4 v[16:19], v[78:79], off
	s_nop 0
	v_addc_co_u32_e32 v81, vcc, 0, v13, vcc
	v_add_co_u32_e32 v88, vcc, 0x1a000000, v12
	global_load_dwordx4 v[20:23], v[80:81], off
	s_nop 0
	v_addc_co_u32_e32 v89, vcc, 0, v13, vcc
	v_add_co_u32_e32 v98, vcc, 0x1a400000, v12
	global_load_dwordx4 v[24:27], v[88:89], off
	s_nop 0
	v_addc_co_u32_e32 v99, vcc, 0, v13, vcc
	v_add_co_u32_e32 v90, vcc, 0x1a800000, v12
	global_load_dwordx4 v[28:31], v[98:99], off
	s_nop 0
	v_addc_co_u32_e32 v91, vcc, 0, v13, vcc
	v_add_co_u32_e32 v82, vcc, 0x1ac00000, v12
	global_load_dwordx4 v[32:35], v[90:91], off
	s_nop 0
	v_addc_co_u32_e32 v83, vcc, 0, v13, vcc
	v_add_co_u32_e32 v92, vcc, 0x1b000000, v12
	global_load_dwordx4 v[36:39], v[82:83], off
	s_nop 0
	v_addc_co_u32_e32 v93, vcc, 0, v13, vcc
	v_add_co_u32_e32 v84, vcc, 0x1b400000, v12
	global_load_dwordx4 v[40:43], v[92:93], off
	s_nop 0
	v_addc_co_u32_e32 v85, vcc, 0, v13, vcc
	v_add_co_u32_e32 v94, vcc, 0x1b800000, v12
	global_load_dwordx4 v[44:47], v[84:85], off
	s_nop 0
	v_addc_co_u32_e32 v95, vcc, 0, v13, vcc
	v_add_co_u32_e32 v86, vcc, 0x1bc00000, v12
	global_load_dwordx4 v[4:7], v[94:95], off
	s_nop 0
	v_addc_co_u32_e32 v87, vcc, 0, v13, vcc
	global_load_dwordx4 v[8:11], v[86:87], off
	v_add_co_u32_e32 v96, vcc, 0x1c000000, v12
	v_lshl_add_u64 v[74:75], v[74:75], 0, s[20:21]
	s_nop 0
	v_addc_co_u32_e32 v97, vcc, 0, v13, vcc
	global_load_dwordx4 v[12:15], v[96:97], off
	global_load_dwordx4 v[100:103], v[54:55], off offset:-4096
	global_load_dwordx4 v[48:51], v[76:77], off offset:1024
	global_load_dwordx4 v[104:107], v[78:79], off offset:1024
	global_load_dwordx4 v[108:111], v[80:81], off offset:1024
	global_load_dwordx4 v[112:115], v[88:89], off offset:1024
	global_load_dwordx4 v[116:119], v[98:99], off offset:1024
	global_load_dwordx4 v[120:123], v[90:91], off offset:1024
	global_load_dwordx4 v[124:127], v[82:83], off offset:1024
	global_load_dwordx4 v[128:131], v[92:93], off offset:1024
	global_load_dwordx4 v[132:135], v[84:85], off offset:1024
	global_load_dwordx4 v[136:139], v[94:95], off offset:1024
	global_load_dwordx4 v[140:143], v[86:87], off offset:1024
	global_load_dwordx4 v[144:147], v[96:97], off offset:1024
	s_cmp_gt_i32 s6, 0x83ff
	s_waitcnt vmcnt(0)
	v_pk_add_f32 v[18:19], v[18:19], 0 op_sel_hi:[1,0]
	v_pk_add_f32 v[16:17], v[16:17], 0 op_sel_hi:[1,0]
	v_pk_add_f32 v[18:19], v[18:19], v[22:23]
	v_pk_add_f32 v[16:17], v[16:17], v[20:21]
	v_pk_add_f32 v[18:19], v[18:19], v[26:27]
	v_pk_add_f32 v[16:17], v[16:17], v[24:25]
	v_pk_add_f32 v[18:19], v[18:19], v[30:31]
	v_pk_add_f32 v[16:17], v[16:17], v[28:29]
	v_pk_add_f32 v[18:19], v[18:19], v[34:35]
	v_pk_add_f32 v[16:17], v[16:17], v[32:33]
	v_pk_add_f32 v[18:19], v[18:19], v[38:39]
	v_pk_add_f32 v[16:17], v[16:17], v[36:37]
	v_pk_add_f32 v[18:19], v[18:19], v[42:43]
	v_pk_add_f32 v[16:17], v[16:17], v[40:41]
	v_pk_add_f32 v[18:19], v[18:19], v[46:47]
	v_pk_add_f32 v[16:17], v[16:17], v[44:45]
	v_pk_add_f32 v[6:7], v[18:19], v[6:7]
	v_pk_add_f32 v[4:5], v[16:17], v[4:5]
	v_pk_add_f32 v[6:7], v[6:7], v[10:11]
	v_pk_add_f32 v[4:5], v[4:5], v[8:9]
	v_pk_add_f32 v[6:7], v[6:7], v[14:15]
	v_pk_add_f32 v[4:5], v[4:5], v[12:13]
	v_pk_fma_f32 v[2:3], v[6:7], v[102:103], v[2:3]
	v_pk_fma_f32 v[0:1], v[4:5], v[100:101], v[0:1]
	global_store_dwordx4 v[76:77], v[0:3], off
	global_load_dwordx4 v[4:7], v[54:55], off offset:-3072
	global_load_dwordx4 v[8:11], v[76:77], off offset:2048
	global_load_dwordx4 v[16:19], v[78:79], off offset:2048
	global_load_dwordx4 v[20:23], v[80:81], off offset:2048
	global_load_dwordx4 v[24:27], v[88:89], off offset:2048
	global_load_dwordx4 v[28:31], v[98:99], off offset:2048
	global_load_dwordx4 v[32:35], v[90:91], off offset:2048
	global_load_dwordx4 v[36:39], v[82:83], off offset:2048
	global_load_dwordx4 v[40:43], v[92:93], off offset:2048
	global_load_dwordx4 v[44:47], v[84:85], off offset:2048
	global_load_dwordx4 v[100:103], v[94:95], off offset:2048
	global_load_dwordx4 v[148:151], v[86:87], off offset:2048
	global_load_dwordx4 v[152:155], v[96:97], off offset:2048
	v_pk_add_f32 v[12:13], v[106:107], 0 op_sel_hi:[1,0]
	v_pk_add_f32 v[14:15], v[104:105], 0 op_sel_hi:[1,0]
	v_pk_add_f32 v[12:13], v[12:13], v[110:111]
	v_pk_add_f32 v[14:15], v[14:15], v[108:109]
	v_pk_add_f32 v[12:13], v[12:13], v[114:115]
	v_pk_add_f32 v[14:15], v[14:15], v[112:113]
	v_pk_add_f32 v[12:13], v[12:13], v[118:119]
	v_pk_add_f32 v[14:15], v[14:15], v[116:117]
	v_pk_add_f32 v[12:13], v[12:13], v[122:123]
	v_pk_add_f32 v[14:15], v[14:15], v[120:121]
	v_pk_add_f32 v[12:13], v[12:13], v[126:127]
	v_pk_add_f32 v[14:15], v[14:15], v[124:125]
	v_pk_add_f32 v[12:13], v[12:13], v[130:131]
	v_pk_add_f32 v[14:15], v[14:15], v[128:129]
	v_pk_add_f32 v[12:13], v[12:13], v[134:135]
	v_pk_add_f32 v[14:15], v[14:15], v[132:133]
	v_pk_add_f32 v[12:13], v[12:13], v[138:139]
	v_pk_add_f32 v[14:15], v[14:15], v[136:137]
	v_pk_add_f32 v[12:13], v[12:13], v[142:143]
	v_pk_add_f32 v[14:15], v[14:15], v[140:141]
	v_pk_add_f32 v[12:13], v[12:13], v[146:147]
	v_pk_add_f32 v[14:15], v[14:15], v[144:145]
	s_waitcnt vmcnt(12)
; __device__ __forceinline__ void norm_mod_pass(const float* xlat, float* xctx, const float* gvec, const float* modL, int ch_sh, int ch_sc, bf16* H, int nrows, int gw, int NGW, int lane, const bf16* x1a, const bf16* x1b, const float* P, int nsplit, const float* pgate) {
;     ...
;             for (int jj = 0; jj < 4; ++jj) { const int cidx = 4 * lane + 256 * jj; v[jj] = *(const f32x4*)(xctx + (size_t)(r - TLAT) * DM + cidx);
; #pragma unroll
;                 for (int s = 0; s < 11; ++s) { const int se = s < nsplit ? s : nsplit - 1; pp_[jj][s] = *(const f32x4*)(P + ((size_t)se * TCTX + (r - TLAT)) * DM + cidx); } }
;             float ss = 0.f;
; #pragma unroll
;             for (int jj = 0; jj < 4; ++jj) { const int cidx = 4 * lane + 256 * jj; f32x4 a = (f32x4){0.f, 0.f, 0.f, 0.f};
; #pragma unroll
;                 for (int s = 0; s < 11; ++s) a += pp_[jj][s] * (s < nsplit ? 1.f : 0.f);
;                 v[jj] += *(const f32x4*)(pgate + cidx) * a; *(f32x4*)(xctx + (size_t)(r - TLAT) * DM + cidx) = v[jj];
;                 ss += (v[jj].x * v[jj].x + v[jj].y * v[jj].y) + (v[jj].z * v[jj].z + v[jj].w * v[jj].w); }
	v_pk_fma_f32 v[6:7], v[12:13], v[6:7], v[50:51]
	v_pk_fma_f32 v[4:5], v[14:15], v[4:5], v[48:49]
	global_store_dwordx4 v[76:77], v[4:7], off offset:1024
	global_load_dwordx4 v[48:51], v[54:55], off offset:-2048
	global_load_dwordx4 v[12:15], v[76:77], off offset:3072
	global_load_dwordx4 v[104:107], v[78:79], off offset:3072
	s_nop 0
	global_load_dwordx4 v[78:81], v[80:81], off offset:3072
	s_nop 0
	global_load_dwordx4 v[108:111], v[88:89], off offset:3072
	global_load_dwordx4 v[112:115], v[98:99], off offset:3072
	s_nop 0
	global_load_dwordx4 v[88:91], v[90:91], off offset:3072
	s_nop 0
	global_load_dwordx4 v[116:119], v[82:83], off offset:3072
	global_load_dwordx4 v[120:123], v[92:93], off offset:3072
	s_nop 0
	global_load_dwordx4 v[82:85], v[84:85], off offset:3072
	s_nop 0
	global_load_dwordx4 v[92:95], v[94:95], off offset:3072
	s_nop 0
	global_load_dwordx4 v[124:127], v[86:87], off offset:3072
	s_nop 0
	global_load_dwordx4 v[96:99], v[96:97], off offset:3072
	s_waitcnt vmcnt(24)
	v_pk_add_f32 v[18:19], v[18:19], 0 op_sel_hi:[1,0]
	v_pk_add_f32 v[16:17], v[16:17], 0 op_sel_hi:[1,0]
	s_waitcnt vmcnt(23)
	v_pk_add_f32 v[18:19], v[18:19], v[22:23]
	v_pk_add_f32 v[16:17], v[16:17], v[20:21]
	s_waitcnt vmcnt(22)
	v_pk_add_f32 v[18:19], v[18:19], v[26:27]
	v_pk_add_f32 v[16:17], v[16:17], v[24:25]
	s_waitcnt vmcnt(21)
	v_pk_add_f32 v[18:19], v[18:19], v[30:31]
	v_pk_add_f32 v[16:17], v[16:17], v[28:29]
	s_waitcnt vmcnt(20)
	v_pk_add_f32 v[18:19], v[18:19], v[34:35]
	v_pk_add_f32 v[16:17], v[16:17], v[32:33]
	s_waitcnt vmcnt(19)
	v_pk_add_f32 v[18:19], v[18:19], v[38:39]
	v_pk_add_f32 v[16:17], v[16:17], v[36:37]
	s_waitcnt vmcnt(18)
	v_pk_add_f32 v[18:19], v[18:19], v[42:43]
	v_pk_add_f32 v[16:17], v[16:17], v[40:41]
	s_waitcnt vmcnt(17)
	v_pk_add_f32 v[18:19], v[18:19], v[46:47]
	v_pk_add_f32 v[16:17], v[16:17], v[44:45]
	s_waitcnt vmcnt(16)
	v_pk_add_f32 v[18:19], v[18:19], v[102:103]
	v_pk_add_f32 v[16:17], v[16:17], v[100:101]
	s_waitcnt vmcnt(15)
	v_pk_add_f32 v[18:19], v[18:19], v[150:151]
	v_pk_add_f32 v[16:17], v[16:17], v[148:149]
	s_waitcnt vmcnt(14)
	v_pk_add_f32 v[18:19], v[18:19], v[154:155]
	v_pk_add_f32 v[16:17], v[16:17], v[152:153]
	v_lshl_add_u64 v[20:21], s[30:31], 0, v[72:73]
	v_add_co_u32_e32 v28, vcc, s72, v20
	v_pk_mul_f32 v[24:25], v[2:3], v[2:3]
	s_nop 0
	v_addc_co_u32_e32 v29, vcc, 0, v21, vcc
	v_pk_mul_f32 v[26:27], v[0:1], v[0:1]
	v_lshl_add_u64 v[72:73], v[72:73], 0, s[18:19]
	v_pk_mov_b32 v[30:31], v[26:27], v[24:25] op_sel:[1,0]
	v_mov_b32_e32 v27, v25
	v_pk_add_f32 v[24:25], v[26:27], v[30:31]
	v_pk_mul_f32 v[26:27], v[4:5], v[4:5]
	v_pk_add_f32 v[30:31], v[24:25], v[24:25] op_sel:[0,1] op_sel_hi:[1,0]
	v_pk_mul_f32 v[24:25], v[6:7], v[6:7]
	s_waitcnt vmcnt(12)
	v_pk_fma_f32 v[10:11], v[18:19], v[50:51], v[10:11]
	v_pk_fma_f32 v[8:9], v[16:17], v[48:49], v[8:9]
	global_store_dwordx4 v[76:77], v[8:11], off offset:2048
	global_load_dwordx4 v[16:19], v[54:55], off offset:-1024
	s_waitcnt vmcnt(12)
	v_pk_add_f32 v[20:21], v[106:107], 0 op_sel_hi:[1,0]
	v_pk_add_f32 v[22:23], v[104:105], 0 op_sel_hi:[1,0]
	s_waitcnt vmcnt(11)
	v_pk_add_f32 v[20:21], v[20:21], v[80:81]
	v_pk_add_f32 v[22:23], v[22:23], v[78:79]
	s_waitcnt vmcnt(10)
	v_pk_add_f32 v[20:21], v[20:21], v[110:111]
	v_pk_add_f32 v[22:23], v[22:23], v[108:109]
	s_waitcnt vmcnt(9)
	v_pk_add_f32 v[20:21], v[20:21], v[114:115]
	v_pk_add_f32 v[22:23], v[22:23], v[112:113]
	s_waitcnt vmcnt(8)
	v_pk_add_f32 v[20:21], v[20:21], v[90:91]
	v_pk_add_f32 v[22:23], v[22:23], v[88:89]
	s_waitcnt vmcnt(7)
	v_pk_add_f32 v[20:21], v[20:21], v[118:119]
	v_pk_add_f32 v[22:23], v[22:23], v[116:117]
	s_waitcnt vmcnt(6)
	v_pk_add_f32 v[20:21], v[20:21], v[122:123]
	v_pk_add_f32 v[22:23], v[22:23], v[120:121]
	s_waitcnt vmcnt(5)
	v_pk_add_f32 v[20:21], v[20:21], v[84:85]
	v_pk_add_f32 v[22:23], v[22:23], v[82:83]
	s_waitcnt vmcnt(4)
	v_pk_add_f32 v[20:21], v[20:21], v[94:95]
	v_pk_add_f32 v[22:23], v[22:23], v[92:93]
	s_waitcnt vmcnt(3)
	v_pk_add_f32 v[20:21], v[20:21], v[126:127]
	v_pk_add_f32 v[22:23], v[22:23], v[124:125]
	s_waitcnt vmcnt(2)
	v_pk_add_f32 v[20:21], v[20:21], v[98:99]
	v_pk_add_f32 v[22:23], v[22:23], v[96:97]
	v_pk_mov_b32 v[32:33], v[26:27], v[24:25] op_sel:[1,0]
	v_mov_b32_e32 v27, v25
	v_pk_add_f32 v[24:25], v[26:27], v[32:33]
	v_mul_f32_e32 v26, v11, v11
	v_pk_add_f32 v[32:33], v[24:25], v[24:25] op_sel:[0,1] op_sel_hi:[1,0]
	v_mul_f32_e32 v24, v9, v9
	v_pk_fma_f32 v[34:35], v[8:9], v[8:9], v[24:25] op_sel_hi:[1,1,0]
	v_pk_fma_f32 v[36:37], v[10:11], v[10:11], v[26:27] op_sel_hi:[1,1,0]
	s_waitcnt vmcnt(0)
; __device__ __forceinline__ void norm_mod_pass(const float* xlat, float* xctx, const float* gvec, const float* modL, int ch_sh, int ch_sc, bf16* H, int nrows, int gw, int NGW, int lane, const bf16* x1a, const bf16* x1b, const float* P, int nsplit, const float* pgate) {
;     ...
;                 v[jj] += *(const f32x4*)(pgate + cidx) * a; *(f32x4*)(xctx + (size_t)(r - TLAT) * DM + cidx) = v[jj];
;                 ss += (v[jj].x * v[jj].x + v[jj].y * v[jj].y) + (v[jj].z * v[jj].z + v[jj].w * v[jj].w); }
;             ss = wave_sum(ss); const float rs = 1.0f / sqrtf(ss * (1.0f / DM) + EPSN);
; #pragma unroll
;             for (int jj = 0; jj < 4; ++jj) { const int cidx = 4 * lane + 256 * jj; const f32x4 gmv = *(const f32x4*)(gvec + cidx) * (*(const f32x4*)(sc + cidx) + 1.0f);
;                 const f32x4 o = v[jj] * rs * gmv + *(const f32x4*)(sh + cidx); v2u w; w.x = pk2(o.x, o.y); w.y = pk2(o.z, o.w);
;                 *(v2u*)(H + (size_t)r * DM + cidx) = w; }
	v_pk_fma_f32 v[14:15], v[20:21], v[18:19], v[14:15]
	v_pk_fma_f32 v[12:13], v[22:23], v[16:17], v[12:13]
	global_store_dwordx4 v[76:77], v[12:15], off offset:3072
	global_load_dwordx4 v[16:19], v[56:57], off
	global_load_dwordx4 v[20:23], v[52:53], off
	global_load_dwordx4 v[24:27], v[58:59], off
	global_load_dwordx4 v[120:123], v[60:61], off
	global_load_dwordx4 v[124:127], v[52:53], off offset:1024
	global_load_dwordx4 v[128:131], v[62:63], off
	global_load_dwordx4 v[132:135], v[64:65], off
	global_load_dwordx4 v[136:139], v[52:53], off offset:2048
	global_load_dwordx4 v[140:143], v[66:67], off
	global_load_dwordx4 v[144:147], v[68:69], off
	global_load_dwordx4 v[148:151], v[52:53], off offset:3072
	global_load_dwordx4 v[152:155], v[70:71], off
	v_mul_f32_e32 v31, v12, v12
	v_mul_f32_e32 v33, v13, v13
	v_mul_f32_e32 v37, v14, v14
	v_mul_f32_e32 v35, v15, v15
	v_pk_add_f32 v[30:31], v[30:31], v[32:33]
	v_pk_add_f32 v[32:33], v[34:35], v[36:37]
	s_waitcnt vmcnt(11)
	v_pk_add_f32 v[18:19], v[18:19], 1.0 op_sel_hi:[1,0]
	v_pk_add_f32 v[30:31], v[30:31], v[32:33]
	v_pk_add_f32 v[16:17], v[16:17], 1.0 op_sel_hi:[1,0]
	v_add_f32_e32 v30, v30, v31
	s_waitcnt vmcnt(10)
	v_pk_mul_f32 v[18:19], v[22:23], v[18:19]
	v_pk_mul_f32 v[16:17], v[20:21], v[16:17]
	v_add_f32_dpp v30, v30, v30 quad_perm:[1,0,3,2] row_mask:0xf bank_mask:0xf bound_ctrl:1
	s_nop 1
	v_add_f32_dpp v30, v30, v30 quad_perm:[2,3,0,1] row_mask:0xf bank_mask:0xf bound_ctrl:1
	s_nop 1
	v_add_f32_dpp v30, v30, v30 row_half_mirror row_mask:0xf bank_mask:0xf bound_ctrl:1
	s_nop 1
	v_add_f32_dpp v30, v30, v30 row_mirror row_mask:0xf bank_mask:0xf bound_ctrl:1
	s_nop 0
	v_readlane_b32 s2, v30, 16
	v_readlane_b32 s3, v30, 48
	v_readlane_b32 s0, v30, 0
	v_readlane_b32 s1, v30, 32
	v_mov_b32_e32 v30, s2
	v_mov_b32_e32 v31, s3
	v_pk_add_f32 v[30:31], s[0:1], v[30:31]
	s_nop 0
	v_add_f32_e32 v30, v30, v31
	v_fmamk_f32 v30, v30, 0x3a800000, v243
	v_mul_f32_e32 v31, 0x4f800000, v30
	v_cmp_gt_f32_e32 vcc, s71, v30
	s_nop 1
	v_cndmask_b32_e32 v30, v30, v31, vcc
	v_sqrt_f32_e32 v31, v30
	s_nop 0
	v_add_u32_e32 v32, -1, v31
	v_add_u32_e32 v33, 1, v31
	v_fma_f32 v34, -v32, v31, v30
	v_fma_f32 v35, -v33, v31, v30
	v_cmp_ge_f32_e64 s[4:5], 0, v34
	s_nop 1
	v_cndmask_b32_e64 v31, v31, v32, s[4:5]
	v_cmp_lt_f32_e64 s[4:5], 0, v35
	s_nop 1
	v_cndmask_b32_e64 v31, v31, v33, s[4:5]
	v_mul_f32_e32 v32, 0x37800000, v31
	v_cndmask_b32_e32 v31, v31, v32, vcc
	v_cmp_class_f32_e32 vcc, v30, v244
	s_nop 1
	v_cndmask_b32_e32 v30, v31, v30, vcc
	v_div_scale_f32 v31, s[0:1], v30, v30, 1.0
	v_rcp_f32_e32 v33, v31
	v_div_scale_f32 v32, vcc, 1.0, v30, 1.0
	v_fma_f32 v34, -v31, v33, 1.0
	v_fmac_f32_e32 v33, v34, v33
	v_mul_f32_e32 v34, v32, v33
	v_fma_f32 v35, -v31, v34, v32
	v_fmac_f32_e32 v34, v35, v33
	v_fma_f32 v31, -v31, v34, v32
	v_div_fmas_f32 v31, v31, v33, v34
	v_div_fixup_f32 v30, v31, v30, 1.0
	v_pk_mul_f32 v[0:1], v[0:1], v[30:31] op_sel_hi:[1,0]
	v_pk_mul_f32 v[2:3], v[2:3], v[30:31] op_sel_hi:[1,0]
	s_waitcnt vmcnt(9)
	v_pk_fma_f32 v[0:1], v[16:17], v[0:1], v[24:25]
	v_pk_fma_f32 v[2:3], v[18:19], v[2:3], v[26:27]
	v_cvt_pk_bf16_f32 v0, v0, v1
	v_cvt_pk_bf16_f32 v1, v2, v3
	global_store_dwordx2 v[28:29], v[0:1], off
	s_nop 0
	v_pk_mul_f32 v[4:5], v[4:5], v[30:31] op_sel_hi:[1,0]
	v_pk_mul_f32 v[6:7], v[6:7], v[30:31] op_sel_hi:[1,0]
	v_pk_mul_f32 v[8:9], v[8:9], v[30:31] op_sel_hi:[1,0]
	v_pk_mul_f32 v[10:11], v[10:11], v[30:31] op_sel_hi:[1,0]
	v_pk_mul_f32 v[12:13], v[12:13], v[30:31] op_sel_hi:[1,0]
	v_pk_mul_f32 v[14:15], v[14:15], v[30:31] op_sel_hi:[1,0]
	s_waitcnt vmcnt(8)
	v_pk_add_f32 v[2:3], v[122:123], 1.0 op_sel_hi:[1,0]
	v_pk_add_f32 v[0:1], v[120:121], 1.0 op_sel_hi:[1,0]
	s_waitcnt vmcnt(7)
	v_pk_mul_f32 v[2:3], v[126:127], v[2:3]
	v_pk_mul_f32 v[0:1], v[124:125], v[0:1]
	s_waitcnt vmcnt(6)
	v_pk_fma_f32 v[2:3], v[2:3], v[6:7], v[130:131]
	v_pk_fma_f32 v[0:1], v[0:1], v[4:5], v[128:129]
	s_nop 0
	v_cvt_pk_bf16_f32 v0, v0, v1
	v_cvt_pk_bf16_f32 v1, v2, v3
	global_store_dwordx2 v[28:29], v[0:1], off offset:512
	s_nop 0
	s_waitcnt vmcnt(5)
	v_pk_add_f32 v[2:3], v[134:135], 1.0 op_sel_hi:[1,0]
	v_pk_add_f32 v[0:1], v[132:133], 1.0 op_sel_hi:[1,0]
	s_waitcnt vmcnt(4)
	v_pk_mul_f32 v[2:3], v[138:139], v[2:3]
	v_pk_mul_f32 v[0:1], v[136:137], v[0:1]
	s_waitcnt vmcnt(3)
	v_pk_fma_f32 v[2:3], v[10:11], v[2:3], v[142:143]
	v_pk_fma_f32 v[0:1], v[8:9], v[0:1], v[140:141]
	s_nop 0
	v_cvt_pk_bf16_f32 v0, v0, v1
	v_cvt_pk_bf16_f32 v1, v2, v3
	global_store_dwordx2 v[28:29], v[0:1], off offset:1024
	s_nop 0
	s_waitcnt vmcnt(2)
	v_pk_add_f32 v[2:3], v[146:147], 1.0 op_sel_hi:[1,0]
	v_pk_add_f32 v[0:1], v[144:145], 1.0 op_sel_hi:[1,0]
	s_waitcnt vmcnt(1)
	v_pk_mul_f32 v[2:3], v[150:151], v[2:3]
	v_pk_mul_f32 v[0:1], v[148:149], v[0:1]
	s_waitcnt vmcnt(0)
	v_pk_fma_f32 v[2:3], v[14:15], v[2:3], v[154:155]
	v_pk_fma_f32 v[0:1], v[12:13], v[0:1], v[152:153]
	s_nop 0
	v_cvt_pk_bf16_f32 v0, v0, v1
	v_cvt_pk_bf16_f32 v1, v2, v3
	global_store_dwordx2 v[28:29], v[0:1], off offset:1536
	s_cbranch_scc0 .LBB0_617
